# nt policy also on rowpass streaming loads and the sample-attention cache loads
# baseline (speedup 1.0000x reference)
.LBB0_604:
	v_ashrrev_i32_e32 v17, 31, v16
	v_lshl_add_u64 v[20:21], v[16:17], 0, v[56:57]
	v_lshlrev_b64 v[18:19], 11, v[16:17]
	v_lshlrev_b64 v[20:21], 9, v[20:21]
	v_lshl_add_u64 v[20:21], v[58:59], 0, v[20:21]
	v_lshl_add_u64 v[22:23], v[62:63], 0, v[18:19]
	global_load_dwordx4 v[74:77], v[22:23], off nt
	global_load_dwordx4 v[78:81], v[20:21], off nt
	v_lshl_add_u64 v[20:21], v[16:17], 0, v[60:61]
	v_lshlrev_b64 v[20:21], 9, v[20:21]
	v_lshl_add_u64 v[20:21], v[58:59], 0, v[20:21]
	global_load_dwordx4 v[82:85], v[20:21], off nt
	global_load_dwordx4 v[86:89], v[22:23], off offset:1024 nt
	v_add_u32_e32 v66, s9, v16
	v_add_u32_e32 v70, s10, v16
	v_add_u32_e32 v68, s11, v16
	v_min_i32_e32 v16, 0x407f, v66
	v_ashrrev_i32_e32 v17, 31, v16
	v_lshl_add_u64 v[26:27], v[16:17], 0, v[56:57]
	v_lshlrev_b64 v[26:27], 9, v[26:27]
	v_lshl_add_u64 v[26:27], v[58:59], 0, v[26:27]
	global_load_dwordx4 v[98:101], v[26:27], off nt
	v_min_i32_e32 v20, 0x407f, v70
	v_min_i32_e32 v24, 0x407f, v68
	v_ashrrev_i32_e32 v21, 31, v20
	v_ashrrev_i32_e32 v25, 31, v24
	v_lshl_add_u64 v[72:73], v[64:65], 0, v[18:19]
	v_lshlrev_b64 v[18:19], 11, v[16:17]
	v_lshl_add_u64 v[16:17], v[16:17], 0, v[60:61]
	v_lshlrev_b64 v[28:29], 11, v[20:21]
	v_lshl_add_u64 v[30:31], v[20:21], 0, v[56:57]
	v_lshl_add_u64 v[20:21], v[20:21], 0, v[60:61]
	v_lshlrev_b64 v[32:33], 11, v[24:25]
	v_lshl_add_u64 v[22:23], v[24:25], 0, v[56:57]
	v_lshl_add_u64 v[24:25], v[24:25], 0, v[60:61]
	v_lshl_add_u64 v[106:107], v[62:63], 0, v[18:19]
	v_lshlrev_b64 v[16:17], 9, v[16:17]
	v_lshlrev_b64 v[18:19], 9, v[30:31]
	v_lshlrev_b64 v[20:21], 9, v[20:21]
	v_lshlrev_b64 v[22:23], 9, v[22:23]
	v_lshlrev_b64 v[24:25], 9, v[24:25]
	v_lshl_add_u64 v[108:109], v[62:63], 0, v[28:29]
	v_lshl_add_u64 v[110:111], v[62:63], 0, v[32:33]
	v_lshl_add_u64 v[112:113], v[58:59], 0, v[16:17]
	v_lshl_add_u64 v[114:115], v[58:59], 0, v[18:19]
	v_lshl_add_u64 v[116:117], v[58:59], 0, v[20:21]
	v_lshl_add_u64 v[118:119], v[58:59], 0, v[22:23]
	v_lshl_add_u64 v[120:121], v[58:59], 0, v[24:25]
	global_load_dwordx4 v[52:55], v[106:107], off nt
	global_load_dwordx4 v[102:105], v[112:113], off nt
	global_load_dwordx4 v[48:51], v[106:107], off offset:1024 nt
	global_load_dwordx4 v[44:47], v[114:115], off nt
	global_load_dwordx4 v[36:39], v[108:109], off nt
	s_waitcnt lgkmcnt(0)
	global_load_dwordx4 v[40:43], v[116:117], off nt
	global_load_dwordx4 v[32:35], v[108:109], off offset:1024 nt
	global_load_dwordx4 v[28:31], v[118:119], off nt
	global_load_dwordx4 v[20:23], v[110:111], off nt
	global_load_dwordx4 v[24:27], v[120:121], off nt
	global_load_dwordx4 v[16:19], v[110:111], off offset:1024 nt
	s_waitcnt vmcnt(15)
	v_lshlrev_b32_e32 v106, 16, v77
	s_waitcnt vmcnt(14)
	v_lshlrev_b32_e32 v114, 16, v78
	v_and_b32_e32 v115, 0xffff0000, v78
	v_lshlrev_b32_e32 v112, 16, v79
	v_and_b32_e32 v113, 0xffff0000, v79
	s_waitcnt vmcnt(13)
	v_lshlrev_b32_e32 v116, 16, v85
	v_and_b32_e32 v117, 0xffff0000, v85
	v_lshlrev_b32_e32 v118, 16, v84
	v_and_b32_e32 v119, 0xffff0000, v84
	v_pk_mul_f32 v[84:85], v[114:115], v[114:115]
	v_lshlrev_b32_e32 v120, 16, v83
	v_and_b32_e32 v121, 0xffff0000, v83
	v_lshlrev_b32_e32 v122, 16, v82
	v_and_b32_e32 v123, 0xffff0000, v82
	v_pk_mul_f32 v[82:83], v[112:113], v[112:113]
	v_add_f32_e32 v67, v84, v85
	v_lshlrev_b32_e32 v110, 16, v80
	v_and_b32_e32 v111, 0xffff0000, v80
	v_add_f32_e32 v67, v82, v67
	v_lshlrev_b32_e32 v108, 16, v81
	v_and_b32_e32 v109, 0xffff0000, v81
	v_pk_mul_f32 v[80:81], v[110:111], v[110:111]
	v_add_f32_e32 v67, v83, v67
	v_add_f32_e32 v67, v80, v67
	v_pk_mul_f32 v[78:79], v[108:109], v[108:109]
	v_add_f32_e32 v67, v81, v67
	v_add_f32_e32 v67, v78, v67
	v_pk_mul_f32 v[130:131], v[122:123], v[122:123]
	v_add_f32_e32 v67, v79, v67
	v_add_f32_e32 v67, v130, v67
	v_pk_mul_f32 v[128:129], v[120:121], v[120:121]
	v_add_f32_e32 v67, v131, v67
	v_add_f32_e32 v67, v128, v67
	v_pk_mul_f32 v[126:127], v[118:119], v[118:119]
	v_add_f32_e32 v67, v129, v67
	v_add_f32_e32 v67, v126, v67
	v_pk_mul_f32 v[124:125], v[116:117], v[116:117]
	v_add_f32_e32 v67, v127, v67
	v_add_f32_e32 v67, v124, v67
	v_add_f32_e32 v67, v125, v67
	ds_bpermute_b32 v69, v90, v67
	v_and_b32_e32 v107, 0xffff0000, v77
	v_lshlrev_b32_e32 v124, 16, v76
	v_and_b32_e32 v125, 0xffff0000, v76
	s_waitcnt vmcnt(11)
	v_lshlrev_b32_e32 v76, 16, v98
	s_waitcnt lgkmcnt(0)
	v_add_f32_e32 v67, v67, v69
	ds_bpermute_b32 v69, v91, v67
	v_and_b32_e32 v77, 0xffff0000, v98
	v_lshlrev_b32_e32 v82, 16, v99
	v_and_b32_e32 v83, 0xffff0000, v99
	v_pk_mul_f32 v[98:99], v[76:77], v[76:77]
	s_waitcnt lgkmcnt(0)
	v_add_f32_e32 v67, v67, v69
	ds_bpermute_b32 v69, v92, v67
	v_lshlrev_b32_e32 v126, 16, v75
	v_and_b32_e32 v127, 0xffff0000, v75
	v_lshlrev_b32_e32 v78, 16, v74
	v_and_b32_e32 v79, 0xffff0000, v74
	s_waitcnt lgkmcnt(0)
	v_add_f32_e32 v67, v67, v69
	ds_bpermute_b32 v69, v93, v67
	v_lshlrev_b32_e32 v74, 16, v100
	v_and_b32_e32 v75, 0xffff0000, v100
	v_lshlrev_b32_e32 v80, 16, v101
	v_and_b32_e32 v81, 0xffff0000, v101
	s_waitcnt lgkmcnt(0)
	v_add_f32_e32 v67, v67, v69
	ds_bpermute_b32 v69, v94, v67
	v_pk_mul_f32 v[100:101], v[82:83], v[82:83]
	v_pk_mul_f32 v[136:137], v[74:75], v[74:75]
	v_pk_mul_f32 v[138:139], v[80:81], v[80:81]
	v_lshlrev_b32_e32 v128, 16, v89
	s_waitcnt lgkmcnt(0)
	v_add_f32_e32 v67, v67, v69
	ds_bpermute_b32 v69, v95, v67
	v_and_b32_e32 v129, 0xffff0000, v89
	v_lshlrev_b32_e32 v130, 16, v88
	v_and_b32_e32 v131, 0xffff0000, v88
	s_waitcnt vmcnt(9)
	v_lshlrev_b32_e32 v88, 16, v102
	s_waitcnt lgkmcnt(0)
	v_add_f32_e32 v67, v67, v69
	v_fmamk_f32 v67, v67, 0x3a800000, v96
	v_mul_f32_e32 v69, 0x4b800000, v67
	v_cmp_gt_f32_e32 vcc, s13, v67
	v_and_b32_e32 v89, 0xffff0000, v102
	v_pk_mul_f32 v[142:143], v[88:89], v[88:89]
	v_cndmask_b32_e32 v67, v67, v69, vcc
	v_rsq_f32_e32 v67, v67
	v_lshlrev_b32_e32 v132, 16, v87
	v_and_b32_e32 v133, 0xffff0000, v87
	v_lshlrev_b32_e32 v134, 16, v86
	v_mul_f32_e32 v69, 0x45800000, v67
	v_cndmask_b32_e32 v140, v67, v69, vcc
	v_add_f32_e32 v67, v98, v99
	v_add_f32_e32 v67, v100, v67
	v_add_f32_e32 v67, v101, v67
	v_add_f32_e32 v67, v136, v67
	v_add_f32_e32 v67, v137, v67
	v_add_f32_e32 v67, v138, v67
	v_add_f32_e32 v67, v139, v67
	v_and_b32_e32 v135, 0xffff0000, v86
	v_lshlrev_b32_e32 v86, 16, v103
	v_and_b32_e32 v87, 0xffff0000, v103
	v_add_f32_e32 v67, v142, v67
	v_pk_mul_f32 v[84:85], v[140:141], v[114:115] op_sel_hi:[0,1]
	v_pk_mul_f32 v[102:103], v[86:87], v[86:87]
	v_add_f32_e32 v67, v143, v67
	v_pk_fma_f32 v[114:115], v[4:5], v[84:85], v[78:79]
	v_lshlrev_b32_e32 v84, 16, v104
	v_and_b32_e32 v85, 0xffff0000, v104
	v_add_f32_e32 v67, v102, v67
	v_pk_mul_f32 v[144:145], v[84:85], v[84:85]
	v_add_f32_e32 v67, v103, v67
	v_lshlrev_b32_e32 v78, 16, v105
	v_and_b32_e32 v79, 0xffff0000, v105
	v_add_f32_e32 v67, v144, v67
	v_pk_mul_f32 v[104:105], v[78:79], v[78:79]
	v_add_f32_e32 v67, v145, v67
	v_add_f32_e32 v67, v104, v67
	v_add_f32_e32 v67, v105, v67
	ds_bpermute_b32 v69, v90, v67
	v_pk_mul_f32 v[98:99], v[140:141], v[110:111] op_sel_hi:[0,1]
	v_pk_mul_f32 v[112:113], v[140:141], v[112:113] op_sel_hi:[0,1]
	v_pk_fma_f32 v[102:103], v[0:1], v[98:99], v[124:125]
	v_pk_mul_f32 v[98:99], v[140:141], v[108:109] op_sel_hi:[0,1]
	s_waitcnt lgkmcnt(0)
	v_add_f32_e32 v67, v67, v69
	ds_bpermute_b32 v69, v91, v67
	v_pk_fma_f32 v[100:101], v[6:7], v[112:113], v[126:127]
	v_pk_fma_f32 v[104:105], v[2:3], v[98:99], v[106:107]
	v_cvt_pk_bf16_f32 v98, v114, v115
	v_cvt_pk_bf16_f32 v99, v100, v101
	s_waitcnt lgkmcnt(0)
	v_add_f32_e32 v67, v67, v69
	ds_bpermute_b32 v69, v92, v67
	v_cvt_pk_bf16_f32 v100, v102, v103
	v_cvt_pk_bf16_f32 v101, v104, v105
	global_store_dwordx4 v[72:73], v[98:101], off
	v_pk_mul_f32 v[102:103], v[140:141], v[118:119] op_sel_hi:[0,1]
	s_waitcnt lgkmcnt(0)
	v_add_f32_e32 v67, v67, v69
	ds_bpermute_b32 v69, v93, v67
	v_pk_mul_f32 v[98:99], v[140:141], v[122:123] op_sel_hi:[0,1]
	v_pk_mul_f32 v[100:101], v[140:141], v[120:121] op_sel_hi:[0,1]
	v_pk_mul_f32 v[104:105], v[140:141], v[116:117] op_sel_hi:[0,1]
	v_pk_fma_f32 v[98:99], v[12:13], v[98:99], v[134:135]
	s_waitcnt lgkmcnt(0)
	v_add_f32_e32 v67, v67, v69
	ds_bpermute_b32 v69, v94, v67
	v_pk_fma_f32 v[100:101], v[14:15], v[100:101], v[132:133]
	v_pk_fma_f32 v[102:103], v[8:9], v[102:103], v[130:131]
	v_pk_fma_f32 v[104:105], v[10:11], v[104:105], v[128:129]
	v_cvt_pk_bf16_f32 v98, v98, v99
	s_waitcnt lgkmcnt(0)
	v_add_f32_e32 v67, v67, v69
	ds_bpermute_b32 v69, v95, v67
	v_cvt_pk_bf16_f32 v99, v100, v101
	v_cvt_pk_bf16_f32 v100, v102, v103
	v_cvt_pk_bf16_f32 v101, v104, v105
	v_cmp_gt_i32_e32 vcc, s8, v66
	global_store_dwordx4 v[72:73], v[98:101], off offset:1024
	s_and_saveexec_b64 s[6:7], vcc
	s_cbranch_execz .LBB0_606
	s_waitcnt lgkmcnt(0)
	v_add_f32_e32 v67, v67, v69
	v_fmamk_f32 v67, v67, 0x3a800000, v96
	v_mul_f32_e32 v69, 0x4b800000, v67
	v_cmp_gt_f32_e32 vcc, s13, v67
	v_lshlrev_b32_e32 v100, 16, v52
	v_and_b32_e32 v101, 0xffff0000, v52
	v_cndmask_b32_e32 v67, v67, v69, vcc
	v_rsq_f32_e32 v69, v67
	v_ashrrev_i32_e32 v67, 31, v66
	v_lshlrev_b64 v[72:73], 11, v[66:67]
	v_lshlrev_b32_e32 v52, 16, v53
	v_mul_f32_e32 v67, 0x45800000, v69
	v_cndmask_b32_e32 v98, v69, v67, vcc
	v_and_b32_e32 v53, 0xffff0000, v53
	v_pk_mul_f32 v[82:83], v[98:99], v[82:83] op_sel_hi:[0,1]
	v_pk_fma_f32 v[82:83], v[6:7], v[82:83], v[52:53]
	v_lshlrev_b32_e32 v52, 16, v54
	v_and_b32_e32 v53, 0xffff0000, v54
	v_pk_mul_f32 v[74:75], v[98:99], v[74:75] op_sel_hi:[0,1]
	v_pk_mul_f32 v[76:77], v[98:99], v[76:77] op_sel_hi:[0,1]
	v_pk_fma_f32 v[74:75], v[0:1], v[74:75], v[52:53]
	v_lshlrev_b32_e32 v52, 16, v55
	v_and_b32_e32 v53, 0xffff0000, v55
	v_pk_mul_f32 v[54:55], v[98:99], v[80:81] op_sel_hi:[0,1]
	v_pk_fma_f32 v[76:77], v[4:5], v[76:77], v[100:101]
	v_pk_fma_f32 v[80:81], v[2:3], v[54:55], v[52:53]
	v_cvt_pk_bf16_f32 v52, v76, v77
	v_cvt_pk_bf16_f32 v53, v82, v83
	v_cvt_pk_bf16_f32 v54, v74, v75
	v_cvt_pk_bf16_f32 v55, v80, v81
	v_lshl_add_u64 v[72:73], v[64:65], 0, v[72:73]
	global_store_dwordx4 v[72:73], v[52:55], off
	v_pk_mul_f32 v[74:75], v[98:99], v[84:85] op_sel_hi:[0,1]
	s_waitcnt vmcnt(11)
	v_lshlrev_b32_e32 v52, 16, v48
	v_and_b32_e32 v53, 0xffff0000, v48
	v_pk_mul_f32 v[54:55], v[98:99], v[88:89] op_sel_hi:[0,1]
	v_pk_fma_f32 v[52:53], v[12:13], v[54:55], v[52:53]
	v_lshlrev_b32_e32 v48, 16, v49
	v_and_b32_e32 v49, 0xffff0000, v49
	v_pk_mul_f32 v[54:55], v[98:99], v[86:87] op_sel_hi:[0,1]
	v_pk_fma_f32 v[54:55], v[14:15], v[54:55], v[48:49]
	v_lshlrev_b32_e32 v48, 16, v50
	v_and_b32_e32 v49, 0xffff0000, v50
	v_pk_fma_f32 v[74:75], v[8:9], v[74:75], v[48:49]
	v_lshlrev_b32_e32 v48, 16, v51
	v_and_b32_e32 v49, 0xffff0000, v51
	v_pk_mul_f32 v[50:51], v[98:99], v[78:79] op_sel_hi:[0,1]
	v_pk_fma_f32 v[76:77], v[10:11], v[50:51], v[48:49]
	v_cvt_pk_bf16_f32 v48, v52, v53
	v_cvt_pk_bf16_f32 v49, v54, v55
	v_cvt_pk_bf16_f32 v50, v74, v75
	v_cvt_pk_bf16_f32 v51, v76, v77
	global_store_dwordx4 v[72:73], v[48:51], off offset:1024

.LBB0_2000:
	s_and_b32 s16, s0, 3
	v_writelane_b32 v254, s0, 49
	s_lshl_b32 s0, s16, 9
	v_writelane_b32 v254, s0, 50
	v_writelane_b32 v254, s1, 51
	s_cmpk_gt_i32 s1, 0x1ff
	s_mov_b64 s[0:1], -1
	s_cbranch_scc0 .LBB0_2022
	v_readlane_b32 s0, v254, 15
	v_readlane_b32 s1, v254, 16
	v_mov_b32_e32 v0, v97
	s_load_dwordx2 s[0:1], s[0:1], 0xa8
	v_readlane_b32 s4, v254, 51
	v_mbcnt_lo_u32_b32 v0, -1, v0
	s_add_i32 s2, s4, 0xfffffe00
	v_mbcnt_hi_u32_b32 v12, -1, v0
	v_readlane_b32 s3, v254, 7
	s_lshr_b32 s8, s2, 2
	s_movk_i32 s2, 0x800
	v_add_u32_e32 v8, s3, v12
	s_and_b32 s14, s4, 3
	s_or_b32 s36, s8, 0x4000
	v_cmp_gt_i32_e32 vcc, s2, v8
	s_waitcnt lgkmcnt(0)
	s_barrier
	s_and_saveexec_b64 s[2:3], vcc
	s_cbranch_execz .LBB0_2008
	s_lshl_b32 s4, s36, 9
	s_add_u32 s4, s0, s4
	s_addc_u32 s5, s1, 0
	s_lshl_b32 s15, s14, 6
	s_lshl_b32 s6, s14, 7
	s_add_u32 s4, s4, s6
	s_addc_u32 s5, s5, 0
	s_add_u32 s4, s4, 0x198e0000
	s_addc_u32 s5, s5, 0
	s_lshl_b32 s7, s8, 9
	s_add_u32 s7, s0, s7
	s_addc_u32 s9, s1, 0
	s_add_u32 s6, s7, s6
	s_addc_u32 s7, s9, 0
	s_add_u32 s6, s6, 0x1a8f0000
	v_readlane_b32 s10, v254, 46
	s_addc_u32 s7, s7, 0
	s_lshl_b32 s8, s8, 7
	s_mov_b32 s9, s37
	v_lshl_add_u32 v9, v12, 2, s10
	s_mov_b64 s[10:11], 0
	v_mov_b32_e32 v13, v8
	v_lshrrev_b32_e32 v100, 4, v8
	v_and_b32_e32 v101, 15, v8
	v_lshlrev_b32_e32 v103, 3, v101
	v_lshlrev_b32_e32 v101, 4, v101
	v_readlane_b32 s18, v254, 15
	v_readlane_b32 s19, v254, 16
	s_load_dwordx4 s[20:23], s[18:19], 0x28
	v_add_u32_e32 v102, s8, v100
	s_lshl_b32 s12, s15, 2
	v_lshl_add_u32 v102, v102, 10, v101
	v_add_u32_e32 v102, s12, v102
	s_waitcnt lgkmcnt(0)
	global_load_dwordx4 v[104:107], v102, s[20:21] offset:1024 nt
	global_load_dwordx4 v[108:111], v102, s[22:23] offset:1024 nt
	v_add_u32_e32 v102, 0x4000, v102
	global_load_dwordx4 v[112:115], v102, s[20:21] offset:1024 nt
	global_load_dwordx4 v[116:119], v102, s[22:23] offset:1024 nt
	v_add_u32_e32 v102, 0x4000, v102
	global_load_dwordx4 v[120:123], v102, s[20:21] offset:1024 nt
	global_load_dwordx4 v[124:127], v102, s[22:23] offset:1024 nt
	v_add_u32_e32 v102, 0x4000, v102
	global_load_dwordx4 v[128:131], v102, s[20:21] offset:1024 nt
	global_load_dwordx4 v[132:135], v102, s[22:23] offset:1024 nt
	v_add_u32_e32 v102, 0x4000, v102
	global_load_dwordx4 v[136:139], v102, s[20:21] offset:1024 nt
	global_load_dwordx4 v[140:143], v102, s[22:23] offset:1024 nt
	v_add_u32_e32 v102, 0x4000, v102
	global_load_dwordx4 v[144:147], v102, s[20:21] offset:1024 nt
	global_load_dwordx4 v[148:151], v102, s[22:23] offset:1024 nt
	v_add_u32_e32 v102, 0x4000, v102
	global_load_dwordx4 v[152:155], v102, s[20:21] offset:1024 nt
	global_load_dwordx4 v[156:159], v102, s[22:23] offset:1024 nt
	v_add_u32_e32 v102, 0x4000, v102
	v_cmp_ne_u32_e32 vcc, 15, v100
	s_and_saveexec_b64 s[10:11], vcc
	global_load_dwordx4 v[160:163], v102, s[20:21] offset:1024 nt
	global_load_dwordx4 v[164:167], v102, s[22:23] offset:1024 nt
	s_xor_b64 exec, exec, s[10:11]
	global_load_dwordx2 v[168:169], v103, s[4:5]
	global_load_dwordx2 v[170:171], v103, s[6:7]
	s_waitcnt vmcnt(0)
	v_lshlrev_b32_e32 v160, 16, v168
	v_and_b32_e32 v161, 0xffff0000, v168
	v_lshlrev_b32_e32 v162, 16, v169
	v_and_b32_e32 v163, 0xffff0000, v169
	v_lshlrev_b32_e32 v164, 16, v170
	v_and_b32_e32 v165, 0xffff0000, v170
	v_lshlrev_b32_e32 v166, 16, v171
	v_and_b32_e32 v167, 0xffff0000, v171
	s_mov_b64 exec, s[10:11]
	s_movk_i32 s12, 0x104
	v_mul_lo_u32 v172, v100, s12
	v_lshlrev_b32_e32 v173, 8, v100
	v_add3_u32 v172, s91, v172, v101
	v_add3_u32 v173, s91, v173, v101
	s_waitcnt vmcnt(0)
	ds_write2_b32 v172, v104, v105 offset1:1
	ds_write2_b32 v172, v106, v107 offset0:2 offset1:3
	ds_write_b128 v173, v[108:111] offset:33280
	v_add_u32_e32 v172, 0x1040, v172
	ds_write2_b32 v172, v112, v113 offset1:1
	ds_write2_b32 v172, v114, v115 offset0:2 offset1:3
	ds_write_b128 v173, v[116:119] offset:37376
	v_add_u32_e32 v172, 0x1040, v172
	ds_write2_b32 v172, v120, v121 offset1:1
	ds_write2_b32 v172, v122, v123 offset0:2 offset1:3
	ds_write_b128 v173, v[124:127] offset:41472
	v_add_u32_e32 v172, 0x1040, v172
	ds_write2_b32 v172, v128, v129 offset1:1
	ds_write2_b32 v172, v130, v131 offset0:2 offset1:3
	ds_write_b128 v173, v[132:135] offset:45568
	v_add_u32_e32 v172, 0x1040, v172
	ds_write2_b32 v172, v136, v137 offset1:1
	ds_write2_b32 v172, v138, v139 offset0:2 offset1:3
	ds_write_b128 v173, v[140:143] offset:49664
	v_add_u32_e32 v172, 0x1040, v172
	ds_write2_b32 v172, v144, v145 offset1:1
	ds_write2_b32 v172, v146, v147 offset0:2 offset1:3
	ds_write_b128 v173, v[148:151] offset:53760
	v_add_u32_e32 v172, 0x1040, v172
	ds_write2_b32 v172, v152, v153 offset1:1
	ds_write2_b32 v172, v154, v155 offset0:2 offset1:3
	ds_write_b128 v173, v[156:159] offset:57856
	v_add_u32_e32 v172, 0x1040, v172
	ds_write2_b32 v172, v160, v161 offset1:1
	ds_write2_b32 v172, v162, v163 offset0:2 offset1:3
	ds_write_b128 v173, v[164:167] offset:61952
